# half-specific K-loop barriers + rising MFMA-block priority + loop-top scalar preamble interleaved into the first MFMA block (LDS read addresses as literals)
# baseline (speedup 1.0000x reference)
; #define PG8_STAGE(bufoff, gbase, voff) do { _Pragma("unroll") for (int _i = 0; _i < 2; ++_i) \
;         __builtin_amdgcn_global_load_lds((const unsigned*)((const char*)(gbase) + (voff)[_i]), (PG8_LAS unsigned*)(lds + (bufoff) + ldsw + _i * 8192), 16, 0, AUX_A); } while (0)
; #define PG8_LDA(dst, b, h) do { _Pragma("unroll") for (int m = 0; m < 4; ++m) _Pragma("unroll") for (int k = 0; k < 2; ++k) dst[m][k] = *(const PG8_LAS bf16x8*)(lds + PG8_SA(b, h) + aoff + m * 2048 + k * 1024); } while (0)
; #define PG8_LDB(dst, b, h) do { _Pragma("unroll") for (int n = 0; n < 2; ++n) _Pragma("unroll") for (int k = 0; k < 2; ++k) dst[n][k] = *(const PG8_LAS bf16x8*)(lds + PG8_SB(b, h) + boff + n * 2048 + k * 1024); } while (0)
; #define PG8_MMA(ai, bj, At, Bt) do { __builtin_amdgcn_s_setprio(1); _Pragma("unroll") for (int m = 0; m < 4; ++m) _Pragma("unroll") for (int n = 0; n < 2; ++n) _Pragma("unroll") for (int k = 0; k < 2; ++k) \
;         acc[ai][bj][m][n] = __builtin_amdgcn_mfma_f32_16x16x32_bf16(Bt[n][k], At[m][k], acc[ai][bj][m][n], 0, 0, 0); __builtin_amdgcn_s_setprio(0); } while (0)
; #define PG8_WAIT_V(n) asm volatile("s_waitcnt vmcnt(" #n ")" ::: "memory")
; #define PG8_WAIT_L(n) asm volatile("s_waitcnt lgkmcnt(" #n ")" ::: "memory")
; #define PG8_BAR __builtin_amdgcn_s_barrier()
; #define PG8_SCHED __builtin_amdgcn_sched_barrier(0)
; template <class Epi, class Sched, bool ALIGN_EPI = false, bool SP2 = false>
; __device__ __forceinline__ void gemm_phase(PG8_LAS unsigned char* lds, const Gemm g, const Sched& S, const Epi& E) {
;     ...
;         for (int t = 0; t < nt; t += 2) {
;             const bool last = (t == nt - 2);
;             const char* a1 = PG8_KP(cA, t + 1, rot, nt);
;             const char* a2 = last ? nAr : PG8_KP(cA, t + 2, rot, nt); const char* b2 = last ? nBr : PG8_KP(cB, t + 2, rot, nt);
;             const char* a3 = a2 + kstep; const char* b3 = b2 + kstep;
;             if (last && has_next) S.a_ready(nxt);
;             if constexpr (SP2) {
;             PG8_LDB(B0, 0, 0); PG8_LDB(B1, 0, 1); PG8_SCHED; PG8_LDA(At, 0, 0); PG8_STAGE(PG8_SA(1, 1), a1 + hstep, voffA);
;             PG8_WAIT_V(8); PG8_WAIT_L(0); PG8_BAR; PG8_MMA(0, 0, At, B0); PG8_MMA(0, 1, At, B1); PG8_BAR; PG8_SCHED;
.LBB0_270:
	s_add_i32 m0, s96, 0xc000
	s_add_i32 s69, s96, 0xe000
	v_add_u32_e32 v148, 0x10000, v221
	v_add_u32_e32 v164, 0x14000, v221
	ds_read_b128 v[136:139], v148
	ds_read_b128 v[140:143], v148 offset:1024
	ds_read_b128 v[144:147], v148 offset:2048
	ds_read_b128 v[148:151], v148 offset:3072
	ds_read_b128 v[152:155], v164
	ds_read_b128 v[156:159], v164 offset:1024
	ds_read_b128 v[160:163], v164 offset:2048
	ds_read_b128 v[164:167], v164 offset:3072
	ds_read_b128 v[192:195], v222
	ds_read_b128 v[196:199], v222 offset:1024
	ds_read_b128 v[200:203], v222 offset:2048
	ds_read_b128 v[224:227], v222 offset:3072
	ds_read_b128 v[228:231], v222 offset:4096
	ds_read_b128 v[232:235], v222 offset:5120
	ds_read_b128 v[236:239], v222 offset:6144
	ds_read_b128 v[240:243], v222 offset:7168
	global_load_lds_dwordx4 v[134:135], off
	s_mov_b32 m0, s69
	s_nop 0
	global_load_lds_dwordx4 v[132:133], off
	s_waitcnt vmcnt(8)
	s_waitcnt lgkmcnt(0)
	s_cmp_lg_u64 s[10:11], 0
	s_cbranch_scc1 .Lhb_1
	s_barrier
.Lhb_1:
	s_setprio 1
	s_waitcnt lgkmcnt(0)
	v_mfma_f32_16x16x32_bf16 v[128:131], v[136:139], v[192:195], v[128:131]
	s_add_i32 s81, s29, 2
	s_cmp_lt_u32 s29, 30
	s_cselect_b32 s0, 0, 0xffffffe0
	v_mfma_f32_16x16x32_bf16 v[124:127], v[144:147], v[192:195], v[124:127]
	s_add_i32 s0, s81, s0
	s_ashr_i32 s1, s0, 31
	v_mfma_f32_16x16x32_bf16 v[112:115], v[136:139], v[200:203], v[112:115]
	s_lshl_b64 s[0:1], s[0:1], 7
	s_add_u32 s42, s40, s0
	s_addc_u32 s43, s41, s1
	v_mfma_f32_16x16x32_bf16 v[108:111], v[144:147], v[200:203], v[108:111]
	s_add_u32 s0, s38, s0
	s_addc_u32 s1, s39, s1
	v_mfma_f32_16x16x32_bf16 v[94:97], v[136:139], v[228:231], v[94:97]
	s_cmp_eq_u32 s29, 30
	s_cselect_b32 s59, s49, s43
	s_cselect_b32 s58, s51, s42
	s_cselect_b32 s61, vcc_lo, s1
	s_cselect_b32 s60, vcc_hi, s0
	v_mfma_f32_16x16x32_bf16 v[90:93], v[144:147], v[228:231], v[90:93]
	s_add_i32 s43, 0, 0x10000
	s_add_i32 s97, s43, s70
	v_mfma_f32_16x16x32_bf16 v[78:81], v[136:139], v[236:239], v[78:81]
	s_add_i32 s46, 0, 0x14000
	s_add_i32 s84, s97, 0x2000
	v_mfma_f32_16x16x32_bf16 v[74:77], v[144:147], v[236:239], v[74:77]
	s_add_u32 s62, s60, 0x80000
	s_addc_u32 s63, s61, 0
	s_setprio 2
	v_mfma_f32_16x16x32_bf16 v[128:131], v[140:143], v[196:199], v[128:131]
	s_add_i32 s4, s46, s70
	s_add_i32 s5, s4, 0x2000
	v_mfma_f32_16x16x32_bf16 v[124:127], v[148:151], v[196:199], v[124:127]
	s_add_i32 s1, 0, 0x18000
	s_add_i32 s47, 0, 0x1c000
	v_mfma_f32_16x16x32_bf16 v[112:115], v[140:143], v[224:227], v[112:115]
	s_add_u32 s56, s58, 0x80000
	s_addc_u32 s57, s59, 0
	v_mfma_f32_16x16x32_bf16 v[108:111], v[148:151], v[224:227], v[108:111]
	s_add_i32 s0, s1, s70
	s_add_i32 s89, s0, 0x2000
	v_mfma_f32_16x16x32_bf16 v[94:97], v[140:143], v[232:235], v[94:97]
	s_add_u32 s42, s60, 0x80080
	s_addc_u32 s43, s61, 0
	v_mfma_f32_16x16x32_bf16 v[90:93], v[148:151], v[232:235], v[90:93]
	s_add_i32 s46, s47, s70
	s_add_i32 s92, s46, 0x2000
	v_mfma_f32_16x16x32_bf16 v[78:81], v[140:143], v[240:243], v[78:81]
	v_mfma_f32_16x16x32_bf16 v[74:77], v[148:151], v[240:243], v[74:77]
	v_mfma_f32_16x16x32_bf16 v[120:123], v[152:155], v[192:195], v[120:123]
	v_mfma_f32_16x16x32_bf16 v[116:119], v[160:163], v[192:195], v[116:119]
	v_mfma_f32_16x16x32_bf16 v[104:107], v[152:155], v[200:203], v[104:107]
	v_mfma_f32_16x16x32_bf16 v[100:103], v[160:163], v[200:203], v[100:103]
	s_setprio 3
	v_mfma_f32_16x16x32_bf16 v[86:89], v[152:155], v[228:231], v[86:89]
	v_mfma_f32_16x16x32_bf16 v[82:85], v[160:163], v[228:231], v[82:85]
	v_mfma_f32_16x16x32_bf16 v[70:73], v[152:155], v[236:239], v[70:73]
	v_mfma_f32_16x16x32_bf16 v[66:69], v[160:163], v[236:239], v[66:69]
	v_mfma_f32_16x16x32_bf16 v[120:123], v[156:159], v[196:199], v[120:123]
	v_mfma_f32_16x16x32_bf16 v[116:119], v[164:167], v[196:199], v[116:119]
	v_mfma_f32_16x16x32_bf16 v[104:107], v[156:159], v[224:227], v[104:107]
	v_mfma_f32_16x16x32_bf16 v[100:103], v[164:167], v[224:227], v[100:103]
	v_mfma_f32_16x16x32_bf16 v[86:89], v[156:159], v[232:235], v[86:89]
	v_mfma_f32_16x16x32_bf16 v[82:85], v[164:167], v[232:235], v[82:85]
	v_mfma_f32_16x16x32_bf16 v[70:73], v[156:159], v[240:243], v[70:73]
	v_mfma_f32_16x16x32_bf16 v[66:69], v[164:167], v[240:243], v[66:69]
	s_setprio 0
	s_cmp_eq_u64 s[10:11], 0
	s_cbranch_scc1 .Lhb_5
	s_barrier

; #define PG8_STAGE(bufoff, gbase, voff) do { _Pragma("unroll") for (int _i = 0; _i < 2; ++_i) \
;         __builtin_amdgcn_global_load_lds((const unsigned*)((const char*)(gbase) + (voff)[_i]), (PG8_LAS unsigned*)(lds + (bufoff) + ldsw + _i * 8192), 16, 0, AUX_A); } while (0)
; #define PG8_LDA(dst, b, h) do { _Pragma("unroll") for (int m = 0; m < 4; ++m) _Pragma("unroll") for (int k = 0; k < 2; ++k) dst[m][k] = *(const PG8_LAS bf16x8*)(lds + PG8_SA(b, h) + aoff + m * 2048 + k * 1024); } while (0)
; #define PG8_LDB(dst, b, h) do { _Pragma("unroll") for (int n = 0; n < 2; ++n) _Pragma("unroll") for (int k = 0; k < 2; ++k) dst[n][k] = *(const PG8_LAS bf16x8*)(lds + PG8_SB(b, h) + boff + n * 2048 + k * 1024); } while (0)
; #define PG8_MMA(ai, bj, At, Bt) do { __builtin_amdgcn_s_setprio(1); _Pragma("unroll") for (int m = 0; m < 4; ++m) _Pragma("unroll") for (int n = 0; n < 2; ++n) _Pragma("unroll") for (int k = 0; k < 2; ++k) \
;         acc[ai][bj][m][n] = __builtin_amdgcn_mfma_f32_16x16x32_bf16(Bt[n][k], At[m][k], acc[ai][bj][m][n], 0, 0, 0); __builtin_amdgcn_s_setprio(0); } while (0)
; #define PG8_WAIT_V(n) asm volatile("s_waitcnt vmcnt(" #n ")" ::: "memory")
; #define PG8_WAIT_L(n) asm volatile("s_waitcnt lgkmcnt(" #n ")" ::: "memory")
; #define PG8_BAR __builtin_amdgcn_s_barrier()
; #define PG8_SCHED __builtin_amdgcn_sched_barrier(0)
; template <class Epi, class Sched, bool ALIGN_EPI = false, bool SP2 = false>
; __device__ __forceinline__ void gemm_phase(PG8_LAS unsigned char* lds, const Gemm g, const Sched& S, const Epi& E) {
;     ...
;             PG8_LDB(B0, 1, 0); PG8_LDB(B1, 1, 1); PG8_SCHED; PG8_LDA(At, 1, 0); PG8_STAGE(PG8_SA(0, 1), a2 + hstep, voffA);
;             PG8_WAIT_V(8); PG8_WAIT_L(0); PG8_BAR; PG8_MMA(0, 0, At, B0); PG8_MMA(0, 1, At, B1); PG8_BAR; PG8_SCHED;
.Lhb_6:
	v_add_u32_e32 v148, 0x18000, v221
	v_add_u32_e32 v164, 0x1c000, v221
	ds_read_b128 v[136:139], v148
	ds_read_b128 v[140:143], v148 offset:1024
	ds_read_b128 v[144:147], v148 offset:2048
	ds_read_b128 v[148:151], v148 offset:3072
	ds_read_b128 v[152:155], v164
	ds_read_b128 v[156:159], v164 offset:1024
	ds_read_b128 v[160:163], v164 offset:2048
	ds_read_b128 v[164:167], v164 offset:3072
	s_mov_b32 m0, s33
	v_lshl_add_u64 v[168:169], s[56:57], 0, v[186:187]
	ds_read_b128 v[192:195], v222 offset:32768
	ds_read_b128 v[196:199], v222 offset:33792
	ds_read_b128 v[200:203], v222 offset:34816
	ds_read_b128 v[224:227], v222 offset:35840
	ds_read_b128 v[228:231], v222 offset:36864
	ds_read_b128 v[232:235], v222 offset:37888
	ds_read_b128 v[236:239], v222 offset:38912
	ds_read_b128 v[240:243], v222 offset:39936
	global_load_lds_dwordx4 v[168:169], off
	v_lshl_add_u64 v[168:169], s[56:57], 0, v[182:183]
	s_mov_b32 m0, s30
	s_nop 0
	global_load_lds_dwordx4 v[168:169], off
	s_waitcnt vmcnt(8)
	s_waitcnt lgkmcnt(0)
	s_cmp_lg_u64 s[10:11], 0
	s_cbranch_scc1 .Lhb_3
	s_barrier

; #define PG8_STAGE(bufoff, gbase, voff) do { _Pragma("unroll") for (int _i = 0; _i < 2; ++_i) \
;         __builtin_amdgcn_global_load_lds((const unsigned*)((const char*)(gbase) + (voff)[_i]), (PG8_LAS unsigned*)(lds + (bufoff) + ldsw + _i * 8192), 16, 0, AUX_A); } while (0)
; #define PG8_LDA(dst, b, h) do { _Pragma("unroll") for (int m = 0; m < 4; ++m) _Pragma("unroll") for (int k = 0; k < 2; ++k) dst[m][k] = *(const PG8_LAS bf16x8*)(lds + PG8_SA(b, h) + aoff + m * 2048 + k * 1024); } while (0)
; #define PG8_LDB(dst, b, h) do { _Pragma("unroll") for (int n = 0; n < 2; ++n) _Pragma("unroll") for (int k = 0; k < 2; ++k) dst[n][k] = *(const PG8_LAS bf16x8*)(lds + PG8_SB(b, h) + boff + n * 2048 + k * 1024); } while (0)
; #define PG8_MMA(ai, bj, At, Bt) do { __builtin_amdgcn_s_setprio(1); _Pragma("unroll") for (int m = 0; m < 4; ++m) _Pragma("unroll") for (int n = 0; n < 2; ++n) _Pragma("unroll") for (int k = 0; k < 2; ++k) \
;         acc[ai][bj][m][n] = __builtin_amdgcn_mfma_f32_16x16x32_bf16(Bt[n][k], At[m][k], acc[ai][bj][m][n], 0, 0, 0); __builtin_amdgcn_s_setprio(0); } while (0)
; #define PG8_WAIT_V(n) asm volatile("s_waitcnt vmcnt(" #n ")" ::: "memory")
; #define PG8_WAIT_L(n) asm volatile("s_waitcnt lgkmcnt(" #n ")" ::: "memory")
; #define PG8_BAR __builtin_amdgcn_s_barrier()
; #define PG8_SCHED __builtin_amdgcn_sched_barrier(0)
; template <class Epi, class Sched, bool ALIGN_EPI = false, bool SP2 = false>
; __device__ __forceinline__ void gemm_phase(PG8_LAS unsigned char* lds, const Gemm g, const Sched& S, const Epi& E) {
;     ...
;         for (int t = 0; t < nt; t += 2) {
;             const bool last = (t == nt - 2);
;             const char* a1 = PG8_KP(cA, t + 1, rot, nt);
;             const char* a2 = last ? nAr : PG8_KP(cA, t + 2, rot, nt); const char* b2 = last ? nBr : PG8_KP(cB, t + 2, rot, nt);
;             const char* a3 = a2 + kstep; const char* b3 = b2 + kstep;
;             if (last && has_next) S.a_ready(nxt);
;             if constexpr (SP2) {
;             PG8_LDB(B0, 0, 0); PG8_LDB(B1, 0, 1); PG8_SCHED; PG8_LDA(At, 0, 0); PG8_STAGE(PG8_SA(1, 1), a1 + hstep, voffA);
;             PG8_WAIT_V(8); PG8_WAIT_L(0); PG8_BAR; PG8_MMA(0, 0, At, B0); PG8_MMA(0, 1, At, B1); PG8_BAR; PG8_SCHED;
.LBB0_936:
	s_add_i32 m0, s25, 0xc000
	s_add_i32 s82, s25, 0xe000
	v_add_u32_e32 v160, 0x10000, v99
	v_add_u32_e32 v166, 0x14000, v99
	ds_read_b128 v[22:25], v160
	ds_read_b128 v[34:37], v160 offset:1024
	ds_read_b128 v[38:41], v160 offset:2048
	ds_read_b128 v[160:163], v160 offset:3072
	ds_read_b128 v[180:183], v166
	ds_read_b128 v[184:187], v166 offset:1024
	ds_read_b128 v[188:191], v166 offset:2048
	ds_read_b128 v[192:195], v166 offset:3072
	ds_read_b128 v[196:199], v165
	ds_read_b128 v[200:203], v165 offset:1024
	ds_read_b128 v[222:225], v165 offset:2048
	ds_read_b128 v[226:229], v165 offset:3072
	ds_read_b128 v[230:233], v165 offset:4096
	ds_read_b128 v[234:237], v165 offset:5120
	ds_read_b128 v[238:241], v165 offset:6144
	ds_read_b128 v[242:245], v165 offset:7168
	global_load_lds_dwordx4 v[16:17], off
	s_mov_b32 m0, s82
	s_nop 0
	global_load_lds_dwordx4 v[14:15], off
	s_waitcnt vmcnt(8)
	s_waitcnt lgkmcnt(0)
	s_cmp_lg_u64 s[12:13], 0
	s_cbranch_scc1 .Lhb_9
	s_barrier
.Lhb_9:
	s_setprio 1
	s_waitcnt lgkmcnt(0)
	v_mfma_f32_16x16x32_bf16 v[144:147], v[22:25], v[196:199], v[144:147]
	s_add_i32 s81, s29, 2
	s_cmp_lt_u32 s29, 14
	s_cselect_b32 s0, 0, -16
	v_mfma_f32_16x16x32_bf16 v[140:143], v[38:41], v[196:199], v[140:143]
	s_add_i32 s0, s81, s0
	s_ashr_i32 s1, s0, 31
	v_mfma_f32_16x16x32_bf16 v[128:131], v[22:25], v[222:225], v[128:131]
	s_lshl_b64 s[0:1], s[0:1], 7
	s_add_u32 s2, s64, s0
	s_addc_u32 s46, s65, s1
	v_mfma_f32_16x16x32_bf16 v[124:127], v[38:41], v[222:225], v[124:127]
	s_add_u32 s0, s26, s0
	s_addc_u32 s1, s27, s1
	v_mfma_f32_16x16x32_bf16 v[112:115], v[22:25], v[230:233], v[112:115]
	s_cmp_eq_u32 s29, 14
	s_cselect_b32 s57, s15, s46
	s_cselect_b32 s56, s17, s2
	s_cselect_b32 s59, s43, s1
	s_cselect_b32 s58, s78, s0
	v_mfma_f32_16x16x32_bf16 v[108:111], v[38:41], v[230:233], v[108:111]
	s_add_i32 s2, 0, 0x10000
	s_add_i32 s83, s2, s33
	v_mfma_f32_16x16x32_bf16 v[94:97], v[22:25], v[238:241], v[94:97]
	s_add_i32 s46, 0, 0x14000
	s_add_i32 s84, s83, 0x2000
	v_mfma_f32_16x16x32_bf16 v[90:93], v[38:41], v[238:241], v[90:93]
	s_add_u32 s60, s58, 0x40000
	s_addc_u32 s61, s59, 0
	s_setprio 2
	v_mfma_f32_16x16x32_bf16 v[144:147], v[34:37], v[200:203], v[144:147]
	s_add_i32 s88, s46, s33
	s_add_i32 s89, s88, 0x2000
	v_mfma_f32_16x16x32_bf16 v[140:143], v[160:163], v[200:203], v[140:143]
	s_add_i32 s90, 0, 0x18000
	s_add_i32 s91, 0, 0x1c000
	v_mfma_f32_16x16x32_bf16 v[128:131], v[34:37], v[226:229], v[128:131]
	s_add_u32 s54, s56, 0x40000
	s_addc_u32 s55, s57, 0
	v_mfma_f32_16x16x32_bf16 v[124:127], v[160:163], v[226:229], v[124:127]
	s_add_i32 s1, s90, s33
	s_add_i32 s0, s1, 0x2000
	v_mfma_f32_16x16x32_bf16 v[112:115], v[34:37], v[234:237], v[112:115]
	s_add_u32 s52, s58, 0x40080
	s_addc_u32 s53, s59, 0
	v_mfma_f32_16x16x32_bf16 v[108:111], v[160:163], v[234:237], v[108:111]
	s_add_i32 s47, s91, s33
	s_add_i32 s46, s47, 0x2000
	v_mfma_f32_16x16x32_bf16 v[94:97], v[34:37], v[242:245], v[94:97]
	v_mfma_f32_16x16x32_bf16 v[90:93], v[160:163], v[242:245], v[90:93]
	v_mfma_f32_16x16x32_bf16 v[136:139], v[180:183], v[196:199], v[136:139]
	v_mfma_f32_16x16x32_bf16 v[132:135], v[188:191], v[196:199], v[132:135]
	v_mfma_f32_16x16x32_bf16 v[120:123], v[180:183], v[222:225], v[120:123]
	v_mfma_f32_16x16x32_bf16 v[116:119], v[188:191], v[222:225], v[116:119]
	s_setprio 3
	v_mfma_f32_16x16x32_bf16 v[104:107], v[180:183], v[230:233], v[104:107]
	v_mfma_f32_16x16x32_bf16 v[100:103], v[188:191], v[230:233], v[100:103]
	v_mfma_f32_16x16x32_bf16 v[86:89], v[180:183], v[238:241], v[86:89]
	v_mfma_f32_16x16x32_bf16 v[82:85], v[188:191], v[238:241], v[82:85]
	v_mfma_f32_16x16x32_bf16 v[136:139], v[184:187], v[200:203], v[136:139]
	v_mfma_f32_16x16x32_bf16 v[132:135], v[192:195], v[200:203], v[132:135]
	v_mfma_f32_16x16x32_bf16 v[120:123], v[184:187], v[226:229], v[120:123]
	v_mfma_f32_16x16x32_bf16 v[116:119], v[192:195], v[226:229], v[116:119]
	v_mfma_f32_16x16x32_bf16 v[104:107], v[184:187], v[234:237], v[104:107]
	v_mfma_f32_16x16x32_bf16 v[100:103], v[192:195], v[234:237], v[100:103]
	v_mfma_f32_16x16x32_bf16 v[86:89], v[184:187], v[242:245], v[86:89]
	v_mfma_f32_16x16x32_bf16 v[82:85], v[192:195], v[242:245], v[82:85]
	s_setprio 0
	s_cmp_eq_u64 s[12:13], 0
	s_cbranch_scc1 .Lhb_13
	s_barrier

; #define PG8_STAGE(bufoff, gbase, voff) do { _Pragma("unroll") for (int _i = 0; _i < 2; ++_i) \
;         __builtin_amdgcn_global_load_lds((const unsigned*)((const char*)(gbase) + (voff)[_i]), (PG8_LAS unsigned*)(lds + (bufoff) + ldsw + _i * 8192), 16, 0, AUX_A); } while (0)
; #define PG8_LDA(dst, b, h) do { _Pragma("unroll") for (int m = 0; m < 4; ++m) _Pragma("unroll") for (int k = 0; k < 2; ++k) dst[m][k] = *(const PG8_LAS bf16x8*)(lds + PG8_SA(b, h) + aoff + m * 2048 + k * 1024); } while (0)
; #define PG8_LDB(dst, b, h) do { _Pragma("unroll") for (int n = 0; n < 2; ++n) _Pragma("unroll") for (int k = 0; k < 2; ++k) dst[n][k] = *(const PG8_LAS bf16x8*)(lds + PG8_SB(b, h) + boff + n * 2048 + k * 1024); } while (0)
; #define PG8_MMA(ai, bj, At, Bt) do { __builtin_amdgcn_s_setprio(1); _Pragma("unroll") for (int m = 0; m < 4; ++m) _Pragma("unroll") for (int n = 0; n < 2; ++n) _Pragma("unroll") for (int k = 0; k < 2; ++k) \
;         acc[ai][bj][m][n] = __builtin_amdgcn_mfma_f32_16x16x32_bf16(Bt[n][k], At[m][k], acc[ai][bj][m][n], 0, 0, 0); __builtin_amdgcn_s_setprio(0); } while (0)
; #define PG8_WAIT_V(n) asm volatile("s_waitcnt vmcnt(" #n ")" ::: "memory")
; #define PG8_WAIT_L(n) asm volatile("s_waitcnt lgkmcnt(" #n ")" ::: "memory")
; #define PG8_BAR __builtin_amdgcn_s_barrier()
; #define PG8_SCHED __builtin_amdgcn_sched_barrier(0)
; template <class Epi, class Sched, bool ALIGN_EPI = false, bool SP2 = false>
; __device__ __forceinline__ void gemm_phase(PG8_LAS unsigned char* lds, const Gemm g, const Sched& S, const Epi& E) {
;     ...
;             PG8_LDB(B0, 1, 0); PG8_LDB(B1, 1, 1); PG8_SCHED; PG8_LDA(At, 1, 0); PG8_STAGE(PG8_SA(0, 1), a2 + hstep, voffA);
;             PG8_WAIT_V(8); PG8_WAIT_L(0); PG8_BAR; PG8_MMA(0, 0, At, B0); PG8_MMA(0, 1, At, B1); PG8_BAR; PG8_SCHED;
.Lhb_14:
	v_add_u32_e32 v160, 0x18000, v99
	v_add_u32_e32 v192, 0x1c000, v99
	ds_read_b128 v[54:57], v160
	ds_read_b128 v[66:69], v160 offset:1024
	ds_read_b128 v[70:73], v160 offset:2048
	ds_read_b128 v[160:163], v160 offset:3072
	ds_read_b128 v[180:183], v192
	ds_read_b128 v[184:187], v192 offset:1024
	ds_read_b128 v[188:191], v192 offset:2048
	ds_read_b128 v[192:195], v192 offset:3072
	s_mov_b32 m0, s63
	v_lshl_add_u64 v[246:247], s[54:55], 0, v[148:149]
	ds_read_b128 v[196:199], v165 offset:32768
	ds_read_b128 v[200:203], v165 offset:33792
	ds_read_b128 v[222:225], v165 offset:34816
	ds_read_b128 v[226:229], v165 offset:35840
	ds_read_b128 v[230:233], v165 offset:36864
	ds_read_b128 v[234:237], v165 offset:37888
	ds_read_b128 v[238:241], v165 offset:38912
	ds_read_b128 v[242:245], v165 offset:39936
	global_load_lds_dwordx4 v[246:247], off
	v_lshl_add_u64 v[246:247], s[54:55], 0, v[152:153]
	s_mov_b32 m0, s69
	s_nop 0
	global_load_lds_dwordx4 v[246:247], off
	s_waitcnt vmcnt(8)
	s_waitcnt lgkmcnt(0)
	s_cmp_lg_u64 s[12:13], 0
	s_cbranch_scc1 .Lhb_11
	s_barrier

; #define PG8_STAGE(bufoff, gbase, voff) do { _Pragma("unroll") for (int _i = 0; _i < 2; ++_i) \
;         __builtin_amdgcn_global_load_lds((const unsigned*)((const char*)(gbase) + (voff)[_i]), (PG8_LAS unsigned*)(lds + (bufoff) + ldsw + _i * 8192), 16, 0, AUX_A); } while (0)
; #define PG8_LDA(dst, b, h) do { _Pragma("unroll") for (int m = 0; m < 4; ++m) _Pragma("unroll") for (int k = 0; k < 2; ++k) dst[m][k] = *(const PG8_LAS bf16x8*)(lds + PG8_SA(b, h) + aoff + m * 2048 + k * 1024); } while (0)
; #define PG8_LDB(dst, b, h) do { _Pragma("unroll") for (int n = 0; n < 2; ++n) _Pragma("unroll") for (int k = 0; k < 2; ++k) dst[n][k] = *(const PG8_LAS bf16x8*)(lds + PG8_SB(b, h) + boff + n * 2048 + k * 1024); } while (0)
; #define PG8_MMA(ai, bj, At, Bt) do { __builtin_amdgcn_s_setprio(1); _Pragma("unroll") for (int m = 0; m < 4; ++m) _Pragma("unroll") for (int n = 0; n < 2; ++n) _Pragma("unroll") for (int k = 0; k < 2; ++k) \
;         acc[ai][bj][m][n] = __builtin_amdgcn_mfma_f32_16x16x32_bf16(Bt[n][k], At[m][k], acc[ai][bj][m][n], 0, 0, 0); __builtin_amdgcn_s_setprio(0); } while (0)
; #define PG8_WAIT_V(n) asm volatile("s_waitcnt vmcnt(" #n ")" ::: "memory")
; #define PG8_WAIT_L(n) asm volatile("s_waitcnt lgkmcnt(" #n ")" ::: "memory")
; #define PG8_BAR __builtin_amdgcn_s_barrier()
; #define PG8_SCHED __builtin_amdgcn_sched_barrier(0)
; template <class Epi, class Sched, bool ALIGN_EPI = false, bool SP2 = false>
; __device__ __forceinline__ void gemm_phase(PG8_LAS unsigned char* lds, const Gemm g, const Sched& S, const Epi& E) {
;     ...
;         for (int t = 0; t < nt; t += 2) {
;             const bool last = (t == nt - 2);
;             const char* a1 = PG8_KP(cA, t + 1, rot, nt);
;             const char* a2 = last ? nAr : PG8_KP(cA, t + 2, rot, nt); const char* b2 = last ? nBr : PG8_KP(cB, t + 2, rot, nt);
;             const char* a3 = a2 + kstep; const char* b3 = b2 + kstep;
;             if (last && has_next) S.a_ready(nxt);
;             if constexpr (SP2) {
;             PG8_LDB(B0, 0, 0); PG8_LDB(B1, 0, 1); PG8_SCHED; PG8_LDA(At, 0, 0); PG8_STAGE(PG8_SA(1, 1), a1 + hstep, voffA);
;             PG8_WAIT_V(8); PG8_WAIT_L(0); PG8_BAR; PG8_MMA(0, 0, At, B0); PG8_MMA(0, 1, At, B1); PG8_BAR; PG8_SCHED;
.LBB0_1067:
	s_add_i32 m0, s71, 0xc000
	s_add_i32 s84, s71, 0xe000
	v_add_u32_e32 v148, 0x10000, v99
	ds_read_b128 v[152:155], v148
	ds_read_b128 v[156:159], v148 offset:1024
	ds_read_b128 v[160:163], v148 offset:2048
	ds_read_b128 v[164:167], v148 offset:3072
	v_add_u32_e32 v148, 0x14000, v99
	ds_read_b128 v[180:183], v148
	ds_read_b128 v[184:187], v148 offset:1024
	ds_read_b128 v[188:191], v148 offset:2048
	ds_read_b128 v[192:195], v148 offset:3072
	ds_read_b128 v[196:199], v151
	ds_read_b128 v[200:203], v151 offset:1024
	ds_read_b128 v[222:225], v151 offset:2048
	ds_read_b128 v[226:229], v151 offset:3072
	ds_read_b128 v[230:233], v151 offset:4096
	ds_read_b128 v[234:237], v151 offset:5120
	ds_read_b128 v[238:241], v151 offset:6144
	ds_read_b128 v[242:245], v151 offset:7168
	global_load_lds_dwordx4 v[146:147], off
	s_mov_b32 m0, s84
	s_nop 0
	global_load_lds_dwordx4 v[144:145], off
	s_waitcnt vmcnt(8)
	s_waitcnt lgkmcnt(0)
	s_cmp_lg_u64 s[12:13], 0
	s_cbranch_scc1 .Lhb_17
	s_barrier
.Lhb_17:
	s_setprio 1
	s_waitcnt lgkmcnt(0)
	v_mfma_f32_16x16x32_bf16 v[128:131], v[152:155], v[196:199], v[128:131]
	s_add_i32 s81, s29, 2
	s_cmp_lt_u32 s29, 14
	s_cselect_b32 s0, 0, -16
	v_mfma_f32_16x16x32_bf16 v[124:127], v[160:163], v[196:199], v[124:127]
	s_add_i32 s0, s81, s0
	s_ashr_i32 s1, s0, 31
	v_mfma_f32_16x16x32_bf16 v[112:115], v[152:155], v[222:225], v[112:115]
	s_lshl_b64 s[0:1], s[0:1], 7
	s_add_u32 s2, s52, s0
	s_addc_u32 s46, s53, s1
	v_mfma_f32_16x16x32_bf16 v[108:111], v[160:163], v[222:225], v[108:111]
	s_add_u32 s0, s42, s0
	s_addc_u32 s1, s43, s1
	v_mfma_f32_16x16x32_bf16 v[94:97], v[152:155], v[230:233], v[94:97]
	s_cmp_eq_u32 s29, 14
	s_cselect_b32 s59, s15, s46
	s_cselect_b32 s58, s17, s2
	s_cselect_b32 s61, s92, s1
	s_cselect_b32 s60, s93, s0
	v_mfma_f32_16x16x32_bf16 v[90:93], v[160:163], v[230:233], v[90:93]
	s_add_i32 s2, 0, 0x10000
	s_add_i32 s94, s2, s70
	v_mfma_f32_16x16x32_bf16 v[78:81], v[152:155], v[238:241], v[78:81]
	s_add_i32 s46, 0, 0x14000
	s_add_i32 s95, s94, 0x2000
	v_mfma_f32_16x16x32_bf16 v[74:77], v[160:163], v[238:241], v[74:77]
	s_add_u32 s62, s60, 0x40000
	s_addc_u32 s63, s61, 0
	s_setprio 2
	v_mfma_f32_16x16x32_bf16 v[128:131], v[156:159], v[200:203], v[128:131]
	s_add_i32 s96, s46, s70
	s_add_i32 s97, s96, 0x2000
	v_mfma_f32_16x16x32_bf16 v[124:127], v[164:167], v[200:203], v[124:127]
	s_add_i32 vcc_lo, 0, 0x18000
	s_add_i32 vcc_hi, 0, 0x1c000
	v_mfma_f32_16x16x32_bf16 v[112:115], v[156:159], v[226:229], v[112:115]
	s_add_u32 s56, s58, 0x40000
	s_addc_u32 s57, s59, 0
	v_mfma_f32_16x16x32_bf16 v[108:111], v[164:167], v[226:229], v[108:111]
	s_add_i32 s1, vcc_lo, s70
	s_add_i32 s0, s1, 0x2000
	v_mfma_f32_16x16x32_bf16 v[94:97], v[156:159], v[234:237], v[94:97]
	s_add_u32 s54, s60, 0x40080
	s_addc_u32 s55, s61, 0
	v_mfma_f32_16x16x32_bf16 v[90:93], v[164:167], v[234:237], v[90:93]
	s_add_i32 s47, vcc_hi, s70
	s_add_i32 s46, s47, 0x2000
	v_mfma_f32_16x16x32_bf16 v[78:81], v[156:159], v[242:245], v[78:81]
	v_mfma_f32_16x16x32_bf16 v[74:77], v[164:167], v[242:245], v[74:77]
	v_mfma_f32_16x16x32_bf16 v[120:123], v[180:183], v[196:199], v[120:123]
	v_mfma_f32_16x16x32_bf16 v[116:119], v[188:191], v[196:199], v[116:119]
	v_mfma_f32_16x16x32_bf16 v[104:107], v[180:183], v[222:225], v[104:107]
	v_mfma_f32_16x16x32_bf16 v[100:103], v[188:191], v[222:225], v[100:103]
	s_setprio 3
	v_mfma_f32_16x16x32_bf16 v[86:89], v[180:183], v[230:233], v[86:89]
	v_mfma_f32_16x16x32_bf16 v[82:85], v[188:191], v[230:233], v[82:85]
	v_mfma_f32_16x16x32_bf16 v[70:73], v[180:183], v[238:241], v[70:73]
	v_mfma_f32_16x16x32_bf16 v[66:69], v[188:191], v[238:241], v[66:69]
	v_mfma_f32_16x16x32_bf16 v[120:123], v[184:187], v[200:203], v[120:123]
	v_mfma_f32_16x16x32_bf16 v[116:119], v[192:195], v[200:203], v[116:119]
	v_mfma_f32_16x16x32_bf16 v[104:107], v[184:187], v[226:229], v[104:107]
	v_mfma_f32_16x16x32_bf16 v[100:103], v[192:195], v[226:229], v[100:103]
	v_mfma_f32_16x16x32_bf16 v[86:89], v[184:187], v[234:237], v[86:89]
	v_mfma_f32_16x16x32_bf16 v[82:85], v[192:195], v[234:237], v[82:85]
	v_mfma_f32_16x16x32_bf16 v[70:73], v[184:187], v[242:245], v[70:73]
	v_mfma_f32_16x16x32_bf16 v[66:69], v[192:195], v[242:245], v[66:69]
	s_setprio 0
	s_cmp_eq_u64 s[12:13], 0
	s_cbranch_scc1 .Lhb_21
	s_barrier

; #define PG8_STAGE(bufoff, gbase, voff) do { _Pragma("unroll") for (int _i = 0; _i < 2; ++_i) \
;         __builtin_amdgcn_global_load_lds((const unsigned*)((const char*)(gbase) + (voff)[_i]), (PG8_LAS unsigned*)(lds + (bufoff) + ldsw + _i * 8192), 16, 0, AUX_A); } while (0)
; #define PG8_LDA(dst, b, h) do { _Pragma("unroll") for (int m = 0; m < 4; ++m) _Pragma("unroll") for (int k = 0; k < 2; ++k) dst[m][k] = *(const PG8_LAS bf16x8*)(lds + PG8_SA(b, h) + aoff + m * 2048 + k * 1024); } while (0)
; #define PG8_LDB(dst, b, h) do { _Pragma("unroll") for (int n = 0; n < 2; ++n) _Pragma("unroll") for (int k = 0; k < 2; ++k) dst[n][k] = *(const PG8_LAS bf16x8*)(lds + PG8_SB(b, h) + boff + n * 2048 + k * 1024); } while (0)
; #define PG8_MMA(ai, bj, At, Bt) do { __builtin_amdgcn_s_setprio(1); _Pragma("unroll") for (int m = 0; m < 4; ++m) _Pragma("unroll") for (int n = 0; n < 2; ++n) _Pragma("unroll") for (int k = 0; k < 2; ++k) \
;         acc[ai][bj][m][n] = __builtin_amdgcn_mfma_f32_16x16x32_bf16(Bt[n][k], At[m][k], acc[ai][bj][m][n], 0, 0, 0); __builtin_amdgcn_s_setprio(0); } while (0)
; #define PG8_WAIT_V(n) asm volatile("s_waitcnt vmcnt(" #n ")" ::: "memory")
; #define PG8_WAIT_L(n) asm volatile("s_waitcnt lgkmcnt(" #n ")" ::: "memory")
; #define PG8_BAR __builtin_amdgcn_s_barrier()
; #define PG8_SCHED __builtin_amdgcn_sched_barrier(0)
; template <class Epi, class Sched, bool ALIGN_EPI = false, bool SP2 = false>
; __device__ __forceinline__ void gemm_phase(PG8_LAS unsigned char* lds, const Gemm g, const Sched& S, const Epi& E) {
;     ...
;         for (int t = 0; t < nt; t += 2) {
;             const bool last = (t == nt - 2);
;             const char* a1 = PG8_KP(cA, t + 1, rot, nt);
;             const char* a2 = last ? nAr : PG8_KP(cA, t + 2, rot, nt); const char* b2 = last ? nBr : PG8_KP(cB, t + 2, rot, nt);
;             const char* a3 = a2 + kstep; const char* b3 = b2 + kstep;
;             if (last && has_next) S.a_ready(nxt);
;             if constexpr (SP2) {
;             PG8_LDB(B0, 0, 0); PG8_LDB(B1, 0, 1); PG8_SCHED; PG8_LDA(At, 0, 0); PG8_STAGE(PG8_SA(1, 1), a1 + hstep, voffA);
;             PG8_WAIT_V(8); PG8_WAIT_L(0); PG8_BAR; PG8_MMA(0, 0, At, B0); PG8_MMA(0, 1, At, B1); PG8_BAR; PG8_SCHED;
.LBB0_1157:
	s_add_i32 m0, s71, 0xc000
	s_add_i32 s84, s71, 0xe000
	v_add_u32_e32 v162, 0x10000, v99
	v_add_u32_e32 v166, 0x14000, v99
	ds_read_b128 v[148:151], v162
	ds_read_b128 v[154:157], v162 offset:1024
	ds_read_b128 v[158:161], v162 offset:2048
	ds_read_b128 v[162:165], v162 offset:3072
	ds_read_b128 v[180:183], v166
	ds_read_b128 v[184:187], v166 offset:1024
	ds_read_b128 v[188:191], v166 offset:2048
	ds_read_b128 v[192:195], v166 offset:3072
	ds_read_b128 v[196:199], v153
	ds_read_b128 v[200:203], v153 offset:1024
	ds_read_b128 v[222:225], v153 offset:2048
	ds_read_b128 v[226:229], v153 offset:3072
	ds_read_b128 v[230:233], v153 offset:4096
	ds_read_b128 v[234:237], v153 offset:5120
	ds_read_b128 v[238:241], v153 offset:6144
	ds_read_b128 v[242:245], v153 offset:7168
	global_load_lds_dwordx4 v[146:147], off
	s_mov_b32 m0, s84
	s_nop 0
	global_load_lds_dwordx4 v[144:145], off
	s_waitcnt vmcnt(8)
	s_waitcnt lgkmcnt(0)
	s_cmp_lg_u64 s[16:17], 0
	s_cbranch_scc1 .Lhb_25
	s_barrier
.Lhb_25:
	s_setprio 1
	s_waitcnt lgkmcnt(0)
	v_mfma_f32_16x16x32_bf16 v[128:131], v[148:151], v[196:199], v[128:131]
	s_add_i32 s81, s29, 2
	s_cmp_lt_u32 s29, 14
	s_cselect_b32 s0, 0, -16
	v_mfma_f32_16x16x32_bf16 v[124:127], v[158:161], v[196:199], v[124:127]
	s_add_i32 s0, s81, s0
	s_ashr_i32 s1, s0, 31
	v_mfma_f32_16x16x32_bf16 v[112:115], v[148:151], v[222:225], v[112:115]
	s_lshl_b64 s[0:1], s[0:1], 7
	s_add_u32 s2, s52, s0
	s_addc_u32 s46, s53, s1
	v_mfma_f32_16x16x32_bf16 v[108:111], v[158:161], v[222:225], v[108:111]
	s_add_u32 s0, s50, s0
	s_addc_u32 s1, s51, s1
	v_mfma_f32_16x16x32_bf16 v[94:97], v[148:151], v[230:233], v[94:97]
	s_cmp_eq_u32 s29, 14
	s_cselect_b32 s59, s19, s46
	s_cselect_b32 s58, s39, s2
	s_cselect_b32 s61, s92, s1
	s_cselect_b32 s60, s93, s0
	v_mfma_f32_16x16x32_bf16 v[90:93], v[158:161], v[230:233], v[90:93]
	s_add_i32 s2, 0, 0x10000
	s_add_i32 s94, s2, s70
	v_mfma_f32_16x16x32_bf16 v[78:81], v[148:151], v[238:241], v[78:81]
	s_add_i32 s46, 0, 0x14000
	s_add_i32 s95, s94, 0x2000
	v_mfma_f32_16x16x32_bf16 v[74:77], v[158:161], v[238:241], v[74:77]
	s_add_u32 s62, s60, 0x40000
	s_addc_u32 s63, s61, 0
	s_setprio 2
	v_mfma_f32_16x16x32_bf16 v[128:131], v[154:157], v[200:203], v[128:131]
	s_add_i32 s96, s46, s70
	s_add_i32 s97, s96, 0x2000
	v_mfma_f32_16x16x32_bf16 v[124:127], v[162:165], v[200:203], v[124:127]
	s_add_i32 vcc_lo, 0, 0x18000
	s_add_i32 vcc_hi, 0, 0x1c000
	v_mfma_f32_16x16x32_bf16 v[112:115], v[154:157], v[226:229], v[112:115]
	s_add_u32 s56, s58, 0x40000
	s_addc_u32 s57, s59, 0
	v_mfma_f32_16x16x32_bf16 v[108:111], v[162:165], v[226:229], v[108:111]
	s_add_i32 s1, vcc_lo, s70
	s_add_i32 s0, s1, 0x2000
	v_mfma_f32_16x16x32_bf16 v[94:97], v[154:157], v[234:237], v[94:97]
	s_add_u32 s54, s60, 0x40080
	s_addc_u32 s55, s61, 0
	v_mfma_f32_16x16x32_bf16 v[90:93], v[162:165], v[234:237], v[90:93]
	s_add_i32 s47, vcc_hi, s70
	s_add_i32 s46, s47, 0x2000
	v_mfma_f32_16x16x32_bf16 v[78:81], v[154:157], v[242:245], v[78:81]
	v_mfma_f32_16x16x32_bf16 v[74:77], v[162:165], v[242:245], v[74:77]
	v_mfma_f32_16x16x32_bf16 v[120:123], v[180:183], v[196:199], v[120:123]
	v_mfma_f32_16x16x32_bf16 v[116:119], v[188:191], v[196:199], v[116:119]
	v_mfma_f32_16x16x32_bf16 v[104:107], v[180:183], v[222:225], v[104:107]
	v_mfma_f32_16x16x32_bf16 v[100:103], v[188:191], v[222:225], v[100:103]
	s_setprio 3
	v_mfma_f32_16x16x32_bf16 v[86:89], v[180:183], v[230:233], v[86:89]
	v_mfma_f32_16x16x32_bf16 v[82:85], v[188:191], v[230:233], v[82:85]
	v_mfma_f32_16x16x32_bf16 v[70:73], v[180:183], v[238:241], v[70:73]
	v_mfma_f32_16x16x32_bf16 v[66:69], v[188:191], v[238:241], v[66:69]
	v_mfma_f32_16x16x32_bf16 v[120:123], v[184:187], v[200:203], v[120:123]
	v_mfma_f32_16x16x32_bf16 v[116:119], v[192:195], v[200:203], v[116:119]
	v_mfma_f32_16x16x32_bf16 v[104:107], v[184:187], v[226:229], v[104:107]
	v_mfma_f32_16x16x32_bf16 v[100:103], v[192:195], v[226:229], v[100:103]
	v_mfma_f32_16x16x32_bf16 v[86:89], v[184:187], v[234:237], v[86:89]
	v_mfma_f32_16x16x32_bf16 v[82:85], v[192:195], v[234:237], v[82:85]
	v_mfma_f32_16x16x32_bf16 v[70:73], v[184:187], v[242:245], v[70:73]
	v_mfma_f32_16x16x32_bf16 v[66:69], v[192:195], v[242:245], v[66:69]
	s_setprio 0
	s_cmp_eq_u64 s[16:17], 0
	s_cbranch_scc1 .Lhb_29
	s_barrier

; #define PG8_STAGE(bufoff, gbase, voff) do { _Pragma("unroll") for (int _i = 0; _i < 2; ++_i) \
;         __builtin_amdgcn_global_load_lds((const unsigned*)((const char*)(gbase) + (voff)[_i]), (PG8_LAS unsigned*)(lds + (bufoff) + ldsw + _i * 8192), 16, 0, AUX_A); } while (0)
; #define PG8_LDA(dst, b, h) do { _Pragma("unroll") for (int m = 0; m < 4; ++m) _Pragma("unroll") for (int k = 0; k < 2; ++k) dst[m][k] = *(const PG8_LAS bf16x8*)(lds + PG8_SA(b, h) + aoff + m * 2048 + k * 1024); } while (0)
; #define PG8_LDB(dst, b, h) do { _Pragma("unroll") for (int n = 0; n < 2; ++n) _Pragma("unroll") for (int k = 0; k < 2; ++k) dst[n][k] = *(const PG8_LAS bf16x8*)(lds + PG8_SB(b, h) + boff + n * 2048 + k * 1024); } while (0)
; #define PG8_MMA(ai, bj, At, Bt) do { __builtin_amdgcn_s_setprio(1); _Pragma("unroll") for (int m = 0; m < 4; ++m) _Pragma("unroll") for (int n = 0; n < 2; ++n) _Pragma("unroll") for (int k = 0; k < 2; ++k) \
;         acc[ai][bj][m][n] = __builtin_amdgcn_mfma_f32_16x16x32_bf16(Bt[n][k], At[m][k], acc[ai][bj][m][n], 0, 0, 0); __builtin_amdgcn_s_setprio(0); } while (0)
; #define PG8_WAIT_V(n) asm volatile("s_waitcnt vmcnt(" #n ")" ::: "memory")
; #define PG8_WAIT_L(n) asm volatile("s_waitcnt lgkmcnt(" #n ")" ::: "memory")
; #define PG8_BAR __builtin_amdgcn_s_barrier()
; #define PG8_SCHED __builtin_amdgcn_sched_barrier(0)
; template <class Epi, class Sched, bool ALIGN_EPI = false, bool SP2 = false>
; __device__ __forceinline__ void gemm_phase(PG8_LAS unsigned char* lds, const Gemm g, const Sched& S, const Epi& E) {
;     ...
;         for (int t = 0; t < nt; t += 2) {
;             const bool last = (t == nt - 2);
;             const char* a1 = PG8_KP(cA, t + 1, rot, nt);
;             const char* a2 = last ? nAr : PG8_KP(cA, t + 2, rot, nt); const char* b2 = last ? nBr : PG8_KP(cB, t + 2, rot, nt);
;             const char* a3 = a2 + kstep; const char* b3 = b2 + kstep;
;             if (last && has_next) S.a_ready(nxt);
;             if constexpr (SP2) {
;             PG8_LDB(B0, 0, 0); PG8_LDB(B1, 0, 1); PG8_SCHED; PG8_LDA(At, 0, 0); PG8_STAGE(PG8_SA(1, 1), a1 + hstep, voffA);
;             PG8_WAIT_V(8); PG8_WAIT_L(0); PG8_BAR; PG8_MMA(0, 0, At, B0); PG8_MMA(0, 1, At, B1); PG8_BAR; PG8_SCHED;
.LBB0_1308:
	s_or_b32 s0, s11, 1
	s_cmp_ge_i32 s0, s71
	s_cselect_b32 s2, s71, 0
	s_add_i32 s11, s11, 2
	s_cmp_ge_i32 s11, s71
	s_cselect_b32 s0, s71, 0
	s_sub_i32 s0, s13, s0
	s_ashr_i32 s1, s0, 31
	s_lshl_b64 s[0:1], s[0:1], 7
	s_add_u32 s15, s40, s0
	s_addc_u32 s29, s41, s1
	s_add_u32 s0, s34, s0
	s_addc_u32 s1, s35, s1
	s_cmp_eq_u32 s71, s13
	s_cselect_b32 s45, s43, s29
	s_cselect_b32 s44, s42, s15
	s_cselect_b32 s37, s19, s1
	s_cselect_b32 s36, s18, s0
	s_add_i32 s15, 0, 0x10000
	s_add_i32 s29, 0, 0x14000
	v_add_u32_e32 v148, 0x10000, v99
	v_add_u32_e32 v168, 0x14000, v99
	ds_read_b128 v[136:139], v148
	ds_read_b128 v[140:143], v148 offset:1024
	ds_read_b128 v[144:147], v148 offset:2048
	ds_read_b128 v[148:151], v148 offset:3072
	ds_read_b128 v[164:167], v168
	ds_read_b128 v[182:185], v168 offset:1024
	ds_read_b128 v[186:189], v168 offset:2048
	ds_read_b128 v[190:193], v168 offset:3072
	v_mad_i64_i32 v[168:169], s[0:1], s2, v220, v[134:135]
	s_add_i32 m0, s50, 0xc000
	ds_read_b128 v[194:197], v181
	ds_read_b128 v[198:201], v181 offset:1024
	ds_read_b128 v[222:225], v181 offset:2048
	ds_read_b128 v[226:229], v181 offset:3072
	ds_read_b128 v[230:233], v181 offset:4096
	ds_read_b128 v[234:237], v181 offset:5120
	ds_read_b128 v[238:241], v181 offset:6144
	ds_read_b128 v[242:245], v181 offset:7168
	global_load_lds_dwordx4 v[168:169], off
	v_mad_i64_i32 v[168:169], s[0:1], s2, v220, v[132:133]
	s_add_i32 m0, s50, 0xe000
	s_nop 0
	global_load_lds_dwordx4 v[168:169], off
	s_waitcnt vmcnt(8)
	s_waitcnt lgkmcnt(0)
	s_cmp_lg_u64 s[8:9], 0
	s_cbranch_scc1 .Lhb_33
	s_barrier

; #define PG8_STAGE(bufoff, gbase, voff) do { _Pragma("unroll") for (int _i = 0; _i < 2; ++_i) \
;         __builtin_amdgcn_global_load_lds((const unsigned*)((const char*)(gbase) + (voff)[_i]), (PG8_LAS unsigned*)(lds + (bufoff) + ldsw + _i * 8192), 16, 0, AUX_A); } while (0)
; #define PG8_LDA(dst, b, h) do { _Pragma("unroll") for (int m = 0; m < 4; ++m) _Pragma("unroll") for (int k = 0; k < 2; ++k) dst[m][k] = *(const PG8_LAS bf16x8*)(lds + PG8_SA(b, h) + aoff + m * 2048 + k * 1024); } while (0)
; #define PG8_LDB(dst, b, h) do { _Pragma("unroll") for (int n = 0; n < 2; ++n) _Pragma("unroll") for (int k = 0; k < 2; ++k) dst[n][k] = *(const PG8_LAS bf16x8*)(lds + PG8_SB(b, h) + boff + n * 2048 + k * 1024); } while (0)
; #define PG8_MMA(ai, bj, At, Bt) do { __builtin_amdgcn_s_setprio(1); _Pragma("unroll") for (int m = 0; m < 4; ++m) _Pragma("unroll") for (int n = 0; n < 2; ++n) _Pragma("unroll") for (int k = 0; k < 2; ++k) \
;         acc[ai][bj][m][n] = __builtin_amdgcn_mfma_f32_16x16x32_bf16(Bt[n][k], At[m][k], acc[ai][bj][m][n], 0, 0, 0); __builtin_amdgcn_s_setprio(0); } while (0)
; #define PG8_WAIT_V(n) asm volatile("s_waitcnt vmcnt(" #n ")" ::: "memory")
; #define PG8_WAIT_L(n) asm volatile("s_waitcnt lgkmcnt(" #n ")" ::: "memory")
; #define PG8_BAR __builtin_amdgcn_s_barrier()
; #define PG8_SCHED __builtin_amdgcn_sched_barrier(0)
; template <class Epi, class Sched, bool ALIGN_EPI = false, bool SP2 = false>
; __device__ __forceinline__ void gemm_phase(PG8_LAS unsigned char* lds, const Gemm g, const Sched& S, const Epi& E) {
;     ...
;             PG8_LDB(B0, 1, 0); PG8_LDB(B1, 1, 1); PG8_SCHED; PG8_LDA(At, 1, 0); PG8_STAGE(PG8_SA(0, 1), a2 + hstep, voffA);
;             PG8_WAIT_V(8); PG8_WAIT_L(0); PG8_BAR; PG8_MMA(0, 0, At, B0); PG8_MMA(0, 1, At, B1); PG8_BAR; PG8_SCHED;
.Lhb_38:
	s_add_i32 s2, 0, 0x18000
	s_add_i32 s15, 0, 0x1c000
	v_add_u32_e32 v148, 0x18000, v99
	v_add_u32_e32 v190, 0x1c000, v99
	ds_read_b128 v[136:139], v148
	ds_read_b128 v[140:143], v148 offset:1024
	ds_read_b128 v[144:147], v148 offset:2048
	ds_read_b128 v[148:151], v148 offset:3072
	ds_read_b128 v[164:167], v190
	ds_read_b128 v[182:185], v190 offset:1024
	ds_read_b128 v[186:189], v190 offset:2048
	ds_read_b128 v[190:193], v190 offset:3072
	s_add_u32 s0, s44, 0x80000
	s_addc_u32 s1, s45, 0
	s_mov_b32 m0, s52
	v_lshl_add_u64 v[246:247], s[0:1], 0, v[158:159]
	ds_read_b128 v[194:197], v181 offset:32768
	ds_read_b128 v[198:201], v181 offset:33792
	ds_read_b128 v[222:225], v181 offset:34816
	ds_read_b128 v[226:229], v181 offset:35840
	ds_read_b128 v[230:233], v181 offset:36864
	ds_read_b128 v[234:237], v181 offset:37888
	ds_read_b128 v[238:241], v181 offset:38912
	ds_read_b128 v[242:245], v181 offset:39936
	global_load_lds_dwordx4 v[246:247], off
	v_lshl_add_u64 v[246:247], s[0:1], 0, v[154:155]
	s_mov_b32 m0, s53
	s_nop 0
	global_load_lds_dwordx4 v[246:247], off
	s_waitcnt vmcnt(8)
	s_waitcnt lgkmcnt(0)
	s_cmp_lg_u64 s[8:9], 0
	s_cbranch_scc1 .Lhb_35
	s_barrier

; #define PG8_STAGE(bufoff, gbase, voff) do { _Pragma("unroll") for (int _i = 0; _i < 2; ++_i) \
;         __builtin_amdgcn_global_load_lds((const unsigned*)((const char*)(gbase) + (voff)[_i]), (PG8_LAS unsigned*)(lds + (bufoff) + ldsw + _i * 8192), 16, 0, AUX_A); } while (0)
; #define PG8_LDA(dst, b, h) do { _Pragma("unroll") for (int m = 0; m < 4; ++m) _Pragma("unroll") for (int k = 0; k < 2; ++k) dst[m][k] = *(const PG8_LAS bf16x8*)(lds + PG8_SA(b, h) + aoff + m * 2048 + k * 1024); } while (0)
; #define PG8_LDB(dst, b, h) do { _Pragma("unroll") for (int n = 0; n < 2; ++n) _Pragma("unroll") for (int k = 0; k < 2; ++k) dst[n][k] = *(const PG8_LAS bf16x8*)(lds + PG8_SB(b, h) + boff + n * 2048 + k * 1024); } while (0)
; #define PG8_MMA(ai, bj, At, Bt) do { __builtin_amdgcn_s_setprio(1); _Pragma("unroll") for (int m = 0; m < 4; ++m) _Pragma("unroll") for (int n = 0; n < 2; ++n) _Pragma("unroll") for (int k = 0; k < 2; ++k) \
;         acc[ai][bj][m][n] = __builtin_amdgcn_mfma_f32_16x16x32_bf16(Bt[n][k], At[m][k], acc[ai][bj][m][n], 0, 0, 0); __builtin_amdgcn_s_setprio(0); } while (0)
; #define PG8_WAIT_V(n) asm volatile("s_waitcnt vmcnt(" #n ")" ::: "memory")
; #define PG8_WAIT_L(n) asm volatile("s_waitcnt lgkmcnt(" #n ")" ::: "memory")
; #define PG8_BAR __builtin_amdgcn_s_barrier()
; #define PG8_SCHED __builtin_amdgcn_sched_barrier(0)
; template <class Epi, class Sched, bool ALIGN_EPI = false, bool SP2 = false>
; __device__ __forceinline__ void gemm_phase(PG8_LAS unsigned char* lds, const Gemm g, const Sched& S, const Epi& E) {
;     ...
;         for (int t = 0; t < nt; t += 2) {
;             const bool last = (t == nt - 2);
;             const char* a1 = PG8_KP(cA, t + 1, rot, nt);
;             const char* a2 = last ? nAr : PG8_KP(cA, t + 2, rot, nt); const char* b2 = last ? nBr : PG8_KP(cB, t + 2, rot, nt);
;             const char* a3 = a2 + kstep; const char* b3 = b2 + kstep;
;             if (last && has_next) S.a_ready(nxt);
;             if constexpr (SP2) {
;             PG8_LDB(B0, 0, 0); PG8_LDB(B1, 0, 1); PG8_SCHED; PG8_LDA(At, 0, 0); PG8_STAGE(PG8_SA(1, 1), a1 + hstep, voffA);
;             PG8_WAIT_V(8); PG8_WAIT_L(0); PG8_BAR; PG8_MMA(0, 0, At, B0); PG8_MMA(0, 1, At, B1); PG8_BAR; PG8_SCHED;
.LBB0_1458:
	s_add_i32 m0, s57, 0xc000
	s_add_i32 s47, s57, 0xe000
	v_add_u32_e32 v162, 0x10000, v99
	v_add_u32_e32 v166, 0x14000, v99
	ds_read_b128 v[150:153], v162
	ds_read_b128 v[154:157], v162 offset:1024
	ds_read_b128 v[158:161], v162 offset:2048
	ds_read_b128 v[162:165], v162 offset:3072
	ds_read_b128 v[180:183], v166
	ds_read_b128 v[184:187], v166 offset:1024
	ds_read_b128 v[188:191], v166 offset:2048
	ds_read_b128 v[192:195], v166 offset:3072
	ds_read_b128 v[196:199], v149
	ds_read_b128 v[200:203], v149 offset:1024
	ds_read_b128 v[222:225], v149 offset:2048
	ds_read_b128 v[226:229], v149 offset:3072
	ds_read_b128 v[230:233], v149 offset:4096
	ds_read_b128 v[234:237], v149 offset:5120
	ds_read_b128 v[238:241], v149 offset:6144
	ds_read_b128 v[242:245], v149 offset:7168
	global_load_lds_dwordx4 v[146:147], off
	s_mov_b32 m0, s47
	s_nop 0
	global_load_lds_dwordx4 v[144:145], off
	s_waitcnt vmcnt(8)
	s_waitcnt lgkmcnt(0)
	s_cmp_lg_u64 s[10:11], 0
	s_cbranch_scc1 .Lhb_41
	s_barrier
.Lhb_41:
	s_setprio 1
	s_waitcnt lgkmcnt(0)
	v_mfma_f32_16x16x32_bf16 v[128:131], v[150:153], v[196:199], v[128:131]
	s_add_i32 s30, s29, 2
	s_cmp_lt_u32 s29, 30
	s_cselect_b32 s0, 0, 0xffffffe0
	v_mfma_f32_16x16x32_bf16 v[120:123], v[158:161], v[196:199], v[120:123]
	s_add_i32 s0, s30, s0
	s_ashr_i32 s1, s0, 31
	v_mfma_f32_16x16x32_bf16 v[112:115], v[150:153], v[222:225], v[112:115]
	s_lshl_b64 s[0:1], s[0:1], 7
	s_add_u32 s2, s40, s0
	s_addc_u32 s31, s41, s1
	v_mfma_f32_16x16x32_bf16 v[104:107], v[158:161], v[222:225], v[104:107]
	s_add_u32 s0, s34, s0
	s_addc_u32 s1, s35, s1
	v_mfma_f32_16x16x32_bf16 v[94:97], v[150:153], v[230:233], v[94:97]
	s_cmp_eq_u32 s29, 30
	s_cselect_b32 s45, s13, s31
	s_cselect_b32 s44, s15, s2
	s_cselect_b32 s49, s71, s1
	s_cselect_b32 s48, s75, s0
	v_mfma_f32_16x16x32_bf16 v[86:89], v[158:161], v[230:233], v[86:89]
	s_add_i32 s2, 0, 0x10000
	s_add_i32 s78, s2, s56
	v_mfma_f32_16x16x32_bf16 v[78:81], v[150:153], v[238:241], v[78:81]
	s_add_i32 s31, 0, 0x14000
	s_add_i32 s81, s78, 0x2000
	v_mfma_f32_16x16x32_bf16 v[70:73], v[158:161], v[238:241], v[70:73]
	s_add_u32 s50, s48, 0x80000
	s_addc_u32 s51, s49, 0
	s_setprio 2
	v_mfma_f32_16x16x32_bf16 v[128:131], v[154:157], v[200:203], v[128:131]
	s_add_i32 s82, s31, s56
	s_add_i32 s83, s82, 0x2000
	v_mfma_f32_16x16x32_bf16 v[120:123], v[162:165], v[200:203], v[120:123]
	s_add_i32 s84, 0, 0x18000
	s_add_i32 s88, 0, 0x1c000
	v_mfma_f32_16x16x32_bf16 v[112:115], v[154:157], v[226:229], v[112:115]
	s_add_u32 s42, s44, 0x80000
	s_addc_u32 s43, s45, 0
	v_mfma_f32_16x16x32_bf16 v[104:107], v[162:165], v[226:229], v[104:107]
	s_add_i32 s1, s84, s56
	s_add_i32 s0, s1, 0x2000
	v_mfma_f32_16x16x32_bf16 v[94:97], v[154:157], v[234:237], v[94:97]
	s_add_u32 s36, s48, 0x80080
	s_addc_u32 s37, s49, 0
	v_mfma_f32_16x16x32_bf16 v[86:89], v[162:165], v[234:237], v[86:89]
	s_add_i32 s46, s88, s56
	s_add_i32 s31, s46, 0x2000
	v_mfma_f32_16x16x32_bf16 v[78:81], v[154:157], v[242:245], v[78:81]
	v_mfma_f32_16x16x32_bf16 v[70:73], v[162:165], v[242:245], v[70:73]
	v_mfma_f32_16x16x32_bf16 v[124:127], v[180:183], v[196:199], v[124:127]
	v_mfma_f32_16x16x32_bf16 v[116:119], v[188:191], v[196:199], v[116:119]
	v_mfma_f32_16x16x32_bf16 v[108:111], v[180:183], v[222:225], v[108:111]
	v_mfma_f32_16x16x32_bf16 v[100:103], v[188:191], v[222:225], v[100:103]
	s_setprio 3
	v_mfma_f32_16x16x32_bf16 v[90:93], v[180:183], v[230:233], v[90:93]
	v_mfma_f32_16x16x32_bf16 v[82:85], v[188:191], v[230:233], v[82:85]
	v_mfma_f32_16x16x32_bf16 v[74:77], v[180:183], v[238:241], v[74:77]
	v_mfma_f32_16x16x32_bf16 v[66:69], v[188:191], v[238:241], v[66:69]
	v_mfma_f32_16x16x32_bf16 v[124:127], v[184:187], v[200:203], v[124:127]
	v_mfma_f32_16x16x32_bf16 v[116:119], v[192:195], v[200:203], v[116:119]
	v_mfma_f32_16x16x32_bf16 v[108:111], v[184:187], v[226:229], v[108:111]
	v_mfma_f32_16x16x32_bf16 v[100:103], v[192:195], v[226:229], v[100:103]
	v_mfma_f32_16x16x32_bf16 v[90:93], v[184:187], v[234:237], v[90:93]
	v_mfma_f32_16x16x32_bf16 v[82:85], v[192:195], v[234:237], v[82:85]
	v_mfma_f32_16x16x32_bf16 v[74:77], v[184:187], v[242:245], v[74:77]
	v_mfma_f32_16x16x32_bf16 v[66:69], v[192:195], v[242:245], v[66:69]
	s_setprio 0
	s_cmp_eq_u64 s[10:11], 0
	s_cbranch_scc1 .Lhb_45
	s_barrier

; #define PG8_STAGE(bufoff, gbase, voff) do { _Pragma("unroll") for (int _i = 0; _i < 2; ++_i) \
;         __builtin_amdgcn_global_load_lds((const unsigned*)((const char*)(gbase) + (voff)[_i]), (PG8_LAS unsigned*)(lds + (bufoff) + ldsw + _i * 8192), 16, 0, AUX_A); } while (0)
; #define PG8_LDA(dst, b, h) do { _Pragma("unroll") for (int m = 0; m < 4; ++m) _Pragma("unroll") for (int k = 0; k < 2; ++k) dst[m][k] = *(const PG8_LAS bf16x8*)(lds + PG8_SA(b, h) + aoff + m * 2048 + k * 1024); } while (0)
; #define PG8_LDB(dst, b, h) do { _Pragma("unroll") for (int n = 0; n < 2; ++n) _Pragma("unroll") for (int k = 0; k < 2; ++k) dst[n][k] = *(const PG8_LAS bf16x8*)(lds + PG8_SB(b, h) + boff + n * 2048 + k * 1024); } while (0)
; #define PG8_MMA(ai, bj, At, Bt) do { __builtin_amdgcn_s_setprio(1); _Pragma("unroll") for (int m = 0; m < 4; ++m) _Pragma("unroll") for (int n = 0; n < 2; ++n) _Pragma("unroll") for (int k = 0; k < 2; ++k) \
;         acc[ai][bj][m][n] = __builtin_amdgcn_mfma_f32_16x16x32_bf16(Bt[n][k], At[m][k], acc[ai][bj][m][n], 0, 0, 0); __builtin_amdgcn_s_setprio(0); } while (0)
; #define PG8_WAIT_V(n) asm volatile("s_waitcnt vmcnt(" #n ")" ::: "memory")
; #define PG8_WAIT_L(n) asm volatile("s_waitcnt lgkmcnt(" #n ")" ::: "memory")
; #define PG8_BAR __builtin_amdgcn_s_barrier()
; #define PG8_SCHED __builtin_amdgcn_sched_barrier(0)
; template <class Epi, class Sched, bool ALIGN_EPI = false, bool SP2 = false>
; __device__ __forceinline__ void gemm_phase(PG8_LAS unsigned char* lds, const Gemm g, const Sched& S, const Epi& E) {
;     ...
;             PG8_LDB(B0, 1, 0); PG8_LDB(B1, 1, 1); PG8_SCHED; PG8_LDA(At, 1, 0); PG8_STAGE(PG8_SA(0, 1), a2 + hstep, voffA);
;             PG8_WAIT_V(8); PG8_WAIT_L(0); PG8_BAR; PG8_MMA(0, 0, At, B0); PG8_MMA(0, 1, At, B1); PG8_BAR; PG8_SCHED;
.Lhb_46:
	v_add_u32_e32 v162, 0x18000, v99
	v_add_u32_e32 v192, 0x1c000, v99
	ds_read_b128 v[150:153], v162
	ds_read_b128 v[154:157], v162 offset:1024
	ds_read_b128 v[158:161], v162 offset:2048
	ds_read_b128 v[162:165], v162 offset:3072
	ds_read_b128 v[180:183], v192
	ds_read_b128 v[184:187], v192 offset:1024
	ds_read_b128 v[188:191], v192 offset:2048
	ds_read_b128 v[192:195], v192 offset:3072
	s_mov_b32 m0, s59
	v_lshl_add_u64 v[246:247], s[42:43], 0, v[138:139]
	ds_read_b128 v[196:199], v149 offset:32768
	ds_read_b128 v[200:203], v149 offset:33792
	ds_read_b128 v[222:225], v149 offset:34816
	ds_read_b128 v[226:229], v149 offset:35840
	ds_read_b128 v[230:233], v149 offset:36864
	ds_read_b128 v[234:237], v149 offset:37888
	ds_read_b128 v[238:241], v149 offset:38912
	ds_read_b128 v[242:245], v149 offset:39936
	global_load_lds_dwordx4 v[246:247], off
	v_lshl_add_u64 v[246:247], s[42:43], 0, v[134:135]
	s_mov_b32 m0, s60
	s_nop 0
	global_load_lds_dwordx4 v[246:247], off
	s_waitcnt vmcnt(8)
	s_waitcnt lgkmcnt(0)
	s_cmp_lg_u64 s[10:11], 0
	s_cbranch_scc1 .Lhb_43
	s_barrier

; #define PG8_STAGE(bufoff, gbase, voff) do { _Pragma("unroll") for (int _i = 0; _i < 2; ++_i) \
;         __builtin_amdgcn_global_load_lds((const unsigned*)((const char*)(gbase) + (voff)[_i]), (PG8_LAS unsigned*)(lds + (bufoff) + ldsw + _i * 8192), 16, 0, AUX_A); } while (0)
; #define PG8_LDA(dst, b, h) do { _Pragma("unroll") for (int m = 0; m < 4; ++m) _Pragma("unroll") for (int k = 0; k < 2; ++k) dst[m][k] = *(const PG8_LAS bf16x8*)(lds + PG8_SA(b, h) + aoff + m * 2048 + k * 1024); } while (0)
; #define PG8_LDB(dst, b, h) do { _Pragma("unroll") for (int n = 0; n < 2; ++n) _Pragma("unroll") for (int k = 0; k < 2; ++k) dst[n][k] = *(const PG8_LAS bf16x8*)(lds + PG8_SB(b, h) + boff + n * 2048 + k * 1024); } while (0)
; #define PG8_MMA(ai, bj, At, Bt) do { __builtin_amdgcn_s_setprio(1); _Pragma("unroll") for (int m = 0; m < 4; ++m) _Pragma("unroll") for (int n = 0; n < 2; ++n) _Pragma("unroll") for (int k = 0; k < 2; ++k) \
;         acc[ai][bj][m][n] = __builtin_amdgcn_mfma_f32_16x16x32_bf16(Bt[n][k], At[m][k], acc[ai][bj][m][n], 0, 0, 0); __builtin_amdgcn_s_setprio(0); } while (0)
; #define PG8_WAIT_V(n) asm volatile("s_waitcnt vmcnt(" #n ")" ::: "memory")
; #define PG8_WAIT_L(n) asm volatile("s_waitcnt lgkmcnt(" #n ")" ::: "memory")
; #define PG8_BAR __builtin_amdgcn_s_barrier()
; #define PG8_SCHED __builtin_amdgcn_sched_barrier(0)
; template <class Epi, class Sched, bool ALIGN_EPI = false, bool SP2 = false>
; __device__ __forceinline__ void gemm_phase(PG8_LAS unsigned char* lds, const Gemm g, const Sched& S, const Epi& E) {
;     ...
;         for (int t = 0; t < nt; t += 2) {
;             const bool last = (t == nt - 2);
;             const char* a1 = PG8_KP(cA, t + 1, rot, nt);
;             const char* a2 = last ? nAr : PG8_KP(cA, t + 2, rot, nt); const char* b2 = last ? nBr : PG8_KP(cB, t + 2, rot, nt);
;             const char* a3 = a2 + kstep; const char* b3 = b2 + kstep;
;             if (last && has_next) S.a_ready(nxt);
;             if constexpr (SP2) {
;             PG8_LDB(B0, 0, 0); PG8_LDB(B1, 0, 1); PG8_SCHED; PG8_LDA(At, 0, 0); PG8_STAGE(PG8_SA(1, 1), a1 + hstep, voffA);
;             PG8_WAIT_V(8); PG8_WAIT_L(0); PG8_BAR; PG8_MMA(0, 0, At, B0); PG8_MMA(0, 1, At, B1); PG8_BAR; PG8_SCHED;
.LBB0_1654:
	s_or_b32 s0, s15, 1
	s_cmp_ge_i32 s0, s82
	s_cselect_b32 s2, s82, 0
	s_add_i32 s15, s15, 2
	s_cmp_ge_i32 s15, s82
	s_cselect_b32 s0, s82, 0
	s_sub_i32 s0, s83, s0
	s_ashr_i32 s1, s0, 31
	s_lshl_b64 s[0:1], s[0:1], 7
	s_add_u32 s29, s38, s0
	s_addc_u32 s42, s39, s1
	s_add_u32 s0, s34, s0
	s_addc_u32 s1, s35, s1
	s_cmp_eq_u32 s82, s83
	s_cselect_b32 s45, s41, s42
	s_cselect_b32 s44, s40, s29
	s_cselect_b32 s43, s19, s1
	s_cselect_b32 s42, s18, s0
	s_add_i32 s29, 0, 0x10000
	s_add_i32 s46, 0, 0x14000
	v_add_u32_e32 v148, 0x10000, v99
	v_add_u32_e32 v168, 0x14000, v99
	ds_read_b128 v[136:139], v148
	ds_read_b128 v[140:143], v148 offset:1024
	ds_read_b128 v[144:147], v148 offset:2048
	ds_read_b128 v[148:151], v148 offset:3072
	ds_read_b128 v[152:155], v168
	ds_read_b128 v[180:183], v168 offset:1024
	ds_read_b128 v[184:187], v168 offset:2048
	ds_read_b128 v[190:193], v168 offset:3072
	v_mad_i64_i32 v[168:169], s[0:1], s2, v220, v[134:135]
	s_add_i32 m0, s50, 0xc000
	ds_read_b128 v[194:197], v189
	ds_read_b128 v[198:201], v189 offset:1024
	ds_read_b128 v[222:225], v189 offset:2048
	ds_read_b128 v[226:229], v189 offset:3072
	ds_read_b128 v[230:233], v189 offset:4096
	ds_read_b128 v[234:237], v189 offset:5120
	ds_read_b128 v[238:241], v189 offset:6144
	ds_read_b128 v[242:245], v189 offset:7168
	global_load_lds_dwordx4 v[168:169], off
	v_mad_i64_i32 v[168:169], s[0:1], s2, v220, v[132:133]
	s_add_i32 m0, s50, 0xe000
	s_nop 0
	global_load_lds_dwordx4 v[168:169], off
	s_waitcnt vmcnt(8)
	s_waitcnt lgkmcnt(0)
	s_cmp_lg_u64 s[12:13], 0
	s_cbranch_scc1 .Lhb_49
	s_barrier

; #define PG8_STAGE(bufoff, gbase, voff) do { _Pragma("unroll") for (int _i = 0; _i < 2; ++_i) \
;         __builtin_amdgcn_global_load_lds((const unsigned*)((const char*)(gbase) + (voff)[_i]), (PG8_LAS unsigned*)(lds + (bufoff) + ldsw + _i * 8192), 16, 0, AUX_A); } while (0)
; #define PG8_LDA(dst, b, h) do { _Pragma("unroll") for (int m = 0; m < 4; ++m) _Pragma("unroll") for (int k = 0; k < 2; ++k) dst[m][k] = *(const PG8_LAS bf16x8*)(lds + PG8_SA(b, h) + aoff + m * 2048 + k * 1024); } while (0)
; #define PG8_LDB(dst, b, h) do { _Pragma("unroll") for (int n = 0; n < 2; ++n) _Pragma("unroll") for (int k = 0; k < 2; ++k) dst[n][k] = *(const PG8_LAS bf16x8*)(lds + PG8_SB(b, h) + boff + n * 2048 + k * 1024); } while (0)
; #define PG8_MMA(ai, bj, At, Bt) do { __builtin_amdgcn_s_setprio(1); _Pragma("unroll") for (int m = 0; m < 4; ++m) _Pragma("unroll") for (int n = 0; n < 2; ++n) _Pragma("unroll") for (int k = 0; k < 2; ++k) \
;         acc[ai][bj][m][n] = __builtin_amdgcn_mfma_f32_16x16x32_bf16(Bt[n][k], At[m][k], acc[ai][bj][m][n], 0, 0, 0); __builtin_amdgcn_s_setprio(0); } while (0)
; #define PG8_WAIT_V(n) asm volatile("s_waitcnt vmcnt(" #n ")" ::: "memory")
; #define PG8_WAIT_L(n) asm volatile("s_waitcnt lgkmcnt(" #n ")" ::: "memory")
; #define PG8_BAR __builtin_amdgcn_s_barrier()
; #define PG8_SCHED __builtin_amdgcn_sched_barrier(0)
; template <class Epi, class Sched, bool ALIGN_EPI = false, bool SP2 = false>
; __device__ __forceinline__ void gemm_phase(PG8_LAS unsigned char* lds, const Gemm g, const Sched& S, const Epi& E) {
;     ...
;             PG8_LDB(B0, 1, 0); PG8_LDB(B1, 1, 1); PG8_SCHED; PG8_LDA(At, 1, 0); PG8_STAGE(PG8_SA(0, 1), a2 + hstep, voffA);
;             PG8_WAIT_V(8); PG8_WAIT_L(0); PG8_BAR; PG8_MMA(0, 0, At, B0); PG8_MMA(0, 1, At, B1); PG8_BAR; PG8_SCHED;
.Lhb_54:
	s_add_i32 s2, 0, 0x18000
	s_add_i32 s29, 0, 0x1c000
	v_add_u32_e32 v148, 0x18000, v99
	v_add_u32_e32 v190, 0x1c000, v99
	ds_read_b128 v[136:139], v148
	ds_read_b128 v[140:143], v148 offset:1024
	ds_read_b128 v[144:147], v148 offset:2048
	ds_read_b128 v[148:151], v148 offset:3072
	ds_read_b128 v[152:155], v190
	ds_read_b128 v[180:183], v190 offset:1024
	ds_read_b128 v[184:187], v190 offset:2048
	ds_read_b128 v[190:193], v190 offset:3072
	s_add_u32 s0, s44, 0x160000
	s_addc_u32 s1, s45, 0
	s_mov_b32 m0, s52
	v_lshl_add_u64 v[246:247], s[0:1], 0, v[162:163]
	ds_read_b128 v[194:197], v189 offset:32768
	ds_read_b128 v[198:201], v189 offset:33792
	ds_read_b128 v[222:225], v189 offset:34816
	ds_read_b128 v[226:229], v189 offset:35840
	ds_read_b128 v[230:233], v189 offset:36864
	ds_read_b128 v[234:237], v189 offset:37888
	ds_read_b128 v[238:241], v189 offset:38912
	ds_read_b128 v[242:245], v189 offset:39936
	global_load_lds_dwordx4 v[246:247], off
	v_lshl_add_u64 v[246:247], s[0:1], 0, v[158:159]
	s_mov_b32 m0, s53
	s_nop 0
	global_load_lds_dwordx4 v[246:247], off
	s_waitcnt vmcnt(8)
	s_waitcnt lgkmcnt(0)
	s_cmp_lg_u64 s[12:13], 0
	s_cbranch_scc1 .Lhb_51
	s_barrier
